# v29
# speedup vs baseline: 1.0005x; 1.0005x over previous
; DEVI void attn_unit(const Params& p, char* lds, int au) {
;     ...
;     if (i == 1) {
;       float mm = fminf(mrun[0], mrun[1]);
; #pragma unroll
;       for (int ofs = 1; ofs < 16; ofs <<= 1) mm = fminf(mm, __shfl_xor(mm, ofs));
;       float* hx = (float*)(lds + 86016);
;       if (lane == 0) hx[wid] = qkb - mm;
;       __syncthreads();
;       const float X = fmaxf(fmaxf(fmaxf(hx[0], hx[1]), fmaxf(hx[2], hx[3])), fmaxf(fmaxf(hx[4], hx[5]), fmaxf(hx[6], hx[7]))) + 152.f;
;       float tf = X / (64.f * slope2) + 1.f;
;       const int tmax = tf > 1000.f ? 1000 : (int)tf;
;       nL = leftAvail < tmax ? leftAvail : tmax;
;       const int nR = rightAvail < tmax ? rightAvail : tmax;
;       total = 2 + nL + nR;
;     }
.LBB0_204:
	s_or_b64 exec, exec, s[14:15]
	v_pk_add_f32 v[138:139], v[146:147], v[138:139]
	v_pk_add_f32 v[120:121], v[152:153], v[120:121]
	v_pk_add_f32 v[114:115], v[114:115], v[138:139]
	v_pk_add_f32 v[106:107], v[106:107], v[120:121]
	v_pk_add_f32 v[114:115], v[154:155], v[114:115]
	v_mov_b32_e32 v63, 0x15010
	v_pk_add_f32 v[138:139], v[148:149], v[114:115]
	v_pk_add_f32 v[114:115], v[116:117], v[118:119]
	s_waitcnt vmcnt(0) lgkmcnt(0)
	v_pk_add_f32 v[118:119], v[108:109], v[114:115]
	s_barrier
	ds_read_b128 v[114:117], v174
	v_pk_add_f32 v[96:97], v[96:97], v[106:107]
	ds_read_b128 v[106:109], v63
	v_mul_f32_e32 v0, 0x42800000, v133
	v_pk_add_f32 v[94:95], v[94:95], v[118:119]
	s_waitcnt lgkmcnt(1)
	v_max_f32_e32 v63, v115, v115
	v_max_f32_e32 v65, v114, v114
	s_waitcnt lgkmcnt(0)
	v_max_f32_e32 v109, v109, v109
	v_max_f32_e32 v108, v108, v108
	v_max_f32_e32 v63, v65, v63
	v_max_f32_e32 v65, v117, v117
	v_max_f32_e32 v114, v116, v116
	v_max_f32_e32 v108, v108, v109
	v_max_f32_e32 v65, v114, v65
	v_max3_f32 v106, v106, v107, v108
	v_max3_f32 v63, v63, v65, v106
	v_add_f32_e32 v63, 0x43180000, v63
	v_div_scale_f32 v65, s[6:7], v0, v0, v63
	v_rcp_f32_e32 v106, v65
	v_pk_add_f32 v[136:137], v[140:141], v[136:137]
	v_pk_add_f32 v[140:141], v[86:87], v[94:95]
	v_pk_add_f32 v[136:137], v[142:143], v[136:137]
	v_fma_f32 v86, -v65, v106, 1.0
	v_fmac_f32_e32 v106, v86, v106
	v_div_scale_f32 v86, vcc, v63, v0, v63
	v_mul_f32_e32 v87, v86, v106
	v_pk_add_f32 v[142:143], v[88:89], v[96:97]
	v_fma_f32 v88, -v65, v87, v86
	v_fmac_f32_e32 v87, v88, v106
	v_fma_f32 v65, -v65, v87, v86
	v_div_fmas_f32 v65, v65, v106, v87
	v_div_fixup_f32 v0, v65, v0, v63
	v_add_f32_e32 v0, 1.0, v0
	s_mov_b32 s6, 0x447a0000
	v_cmp_nle_f32_e32 vcc, s6, v0
	v_mov_b32_e32 v63, 0x447a0000
	s_and_b64 s[2:3], s[2:3], exec
	v_cndmask_b32_e32 v0, v63, v0, vcc
	v_cvt_i32_f32_e32 v0, v0
	s_cselect_b32 s2, 0x100, 32
	s_sub_i32 s2, s2, s19
	v_pk_add_f32 v[136:137], v[144:145], v[136:137]
	v_readfirstlane_b32 s3, v0
	s_min_i32 s6, s76, s3
	s_min_i32 s2, s2, s3
	s_add_i32 s2, s6, s2
	s_add_i32 s7, s2, 2
	v_pk_add_f32 v[136:137], v[150:151], v[136:137]
	s_mov_b32 s11, 2
	s_cmp_lt_i32 s7, 3
	s_barrier
	s_cbranch_scc1 .LBB0_223
	v_readfirstlane_b32 s34, v179
	s_lshl_b32 s8, s18, 1
	v_add_u32_e32 v0, s19, v188
	v_mov_b32_e32 v144, v133
	v_mov_b32_e32 v145, v133
	v_mov_b32_e32 v63, v62
	v_mov_b32_e32 v86, v62
	v_mov_b32_e32 v65, v62
	v_mov_b32_e32 v87, v64
	v_mov_b32_e32 v88, v64
	v_mov_b32_e32 v89, v64
	s_sub_i32 s9, s8, s6
	s_sub_i32 s10, 0, s2
	s_mov_b32 s15, 2
	s_mov_b32 s18, 2

; DEVI void attn_unit(const Params& p, char* lds, int au) {
;     ...
;     if (typeB && i > 0) PVSTEP(lds + 32768 + vprev * 16384);
.LBB0_209:
	s_lshl_b32 s3, s15, 14
	s_addk_i32 s3, 0xc000
	s_cmp_lg_u32 s15, 0
	s_cselect_b32 s3, s3, 0x8000
	v_or_b32_e32 v94, s3, v185
	v_add_u32_e32 v162, v94, v183
	v_add_u32_e32 v163, v94, v184
	ds_read_b128 v[94:97], v162 offset:32768
	ds_read_b128 v[106:109], v162 offset:34816
	ds_read_b128 v[114:117], v163 offset:32768
	ds_read_b128 v[118:121], v163 offset:34816
	ds_read_b128 v[146:149], v162 offset:36864
	ds_read_b128 v[150:153], v162 offset:38912
	ds_read_b128 v[154:157], v163 offset:36864
	ds_read_b128 v[158:161], v163 offset:38912
	s_waitcnt lgkmcnt(0)
	s_setprio 1
	v_mfma_f32_16x16x32_bf16 v[82:85], v[94:97], v[90:93], v[82:85]
	v_mfma_f32_16x16x32_bf16 v[78:81], v[94:97], v[110:113], v[78:81]
	v_mfma_f32_16x16x32_bf16 v[74:77], v[106:109], v[90:93], v[74:77]
	v_mfma_f32_16x16x32_bf16 v[70:73], v[106:109], v[110:113], v[70:73]
	v_mfma_f32_16x16x32_bf16 v[66:69], v[146:149], v[90:93], v[66:69]
	v_mfma_f32_16x16x32_bf16 v[58:61], v[146:149], v[110:113], v[58:61]
	v_mfma_f32_16x16x32_bf16 v[54:57], v[150:153], v[90:93], v[54:57]
	v_mfma_f32_16x16x32_bf16 v[50:53], v[150:153], v[110:113], v[50:53]
	v_mfma_f32_16x16x32_bf16 v[82:85], v[114:117], v[98:101], v[82:85]
	v_mfma_f32_16x16x32_bf16 v[78:81], v[114:117], v[102:105], v[78:81]
	v_mfma_f32_16x16x32_bf16 v[74:77], v[118:121], v[98:101], v[74:77]
	v_mfma_f32_16x16x32_bf16 v[70:73], v[118:121], v[102:105], v[70:73]
	v_mfma_f32_16x16x32_bf16 v[66:69], v[154:157], v[98:101], v[66:69]
	v_mfma_f32_16x16x32_bf16 v[58:61], v[154:157], v[102:105], v[58:61]
	v_mfma_f32_16x16x32_bf16 v[54:57], v[158:161], v[98:101], v[54:57]
	v_mfma_f32_16x16x32_bf16 v[50:53], v[158:161], v[102:105], v[50:53]
	ds_read_b128 v[94:97], v162 offset:40960
	ds_read_b128 v[106:109], v162 offset:43008
	ds_read_b128 v[114:117], v163 offset:40960
	ds_read_b128 v[118:121], v163 offset:43008
	ds_read_b128 v[146:149], v162 offset:45056
	ds_read_b128 v[150:153], v162 offset:47104
	ds_read_b128 v[154:157], v163 offset:45056
	ds_read_b128 v[158:161], v163 offset:47104
	s_waitcnt lgkmcnt(0)
	v_mfma_f32_16x16x32_bf16 v[46:49], v[94:97], v[90:93], v[46:49]
	v_mfma_f32_16x16x32_bf16 v[42:45], v[94:97], v[110:113], v[42:45]
	v_mfma_f32_16x16x32_bf16 v[38:41], v[106:109], v[90:93], v[38:41]
	v_mfma_f32_16x16x32_bf16 v[34:37], v[106:109], v[110:113], v[34:37]
	v_mfma_f32_16x16x32_bf16 v[30:33], v[146:149], v[90:93], v[30:33]
	v_mfma_f32_16x16x32_bf16 v[26:29], v[146:149], v[110:113], v[26:29]
	v_mfma_f32_16x16x32_bf16 v[22:25], v[150:153], v[90:93], v[22:25]
	v_mfma_f32_16x16x32_bf16 v[2:5], v[150:153], v[110:113], v[2:5]
	v_mfma_f32_16x16x32_bf16 v[46:49], v[114:117], v[98:101], v[46:49]
	v_mfma_f32_16x16x32_bf16 v[42:45], v[114:117], v[102:105], v[42:45]
	v_mfma_f32_16x16x32_bf16 v[38:41], v[118:121], v[98:101], v[38:41]
	v_mfma_f32_16x16x32_bf16 v[34:37], v[118:121], v[102:105], v[34:37]
	v_mfma_f32_16x16x32_bf16 v[30:33], v[154:157], v[98:101], v[30:33]
	v_mfma_f32_16x16x32_bf16 v[26:29], v[154:157], v[102:105], v[26:29]
	v_mfma_f32_16x16x32_bf16 v[22:25], v[158:161], v[98:101], v[22:25]
	v_mfma_f32_16x16x32_bf16 v[2:5], v[158:161], v[102:105], v[2:5]
	s_setprio 0
; DEVI f32x4 mfma(bf16x8 a, bf16x8 b, f32x4 c) { return __builtin_amdgcn_mfma_f32_16x16x32_bf16(a, b, c, 0, 0, 0); }
; DEVI void attn_unit(const Params& p, char* lds, int au) {
;     ...
;     const float sgn = (kt < ktw) ? 1.f : ((kt > ktw) ? -1.f : 0.f);
;     f32x4 sc[4][2];
;     float rc[2];
;     rc[0] = sgn * slope2 * ((float)(kt * 64) - qpos[0]);
;     rc[1] = sgn * slope2 * ((float)(kt * 64) - qpos[1]);
;     {
;       bf16x8 kf[4][2];
; #pragma unroll
;       for (int kb = 0; kb < 4; ++kb)
; #pragma unroll
;         for (int kk = 0; kk < 2; ++kk)
;           kf[kb][kk] = *(const bf16x8*)(Ks + (kb * 16 + fr) * 256 + (((mp * 8 + kk * 4 + fq) ^ fr) << 4));
;       const float ss2 = sgn * slope2;
;       const float b0 = sgn * cl0 + rc[0] - mrun[0], b1 = sgn * cl0 + rc[1] - mrun[1];
; #pragma unroll
;       for (int kb = 0; kb < 4; ++kb)
; #pragma unroll
;         for (int j = 0; j < 4; ++j) {
;           sc[kb][0][j] = b0 + ss2 * (float)(kb * 16 + j);
;           sc[kb][1][j] = b1 + ss2 * (float)(kb * 16 + j);
;         }
;       __builtin_amdgcn_sched_barrier(0);
; #pragma unroll
;       for (int kk = 0; kk < 2; ++kk)
; #pragma unroll
;         for (int kb = 0; kb < 4; ++kb) {
;           sc[kb][0] = mfma(kf[kb][kk], qf[0][kk], sc[kb][0]);
;           sc[kb][1] = mfma(kf[kb][kk], qf[1][kk], sc[kb][1]);
;         }
.LBB0_210:
	s_add_i32 s3, s18, -1
	s_add_i32 s18, s8, 1
	s_add_i32 s2, s2, 2
	s_cmp_gt_i32 s3, s6
	s_cselect_b32 s20, s2, s18
	s_lshl_b32 s18, s20, 6
	v_cvt_f32_i32_e32 v90, s18
	v_cmp_gt_i32_e32 vcc, s20, v0
	v_sub_f32_e32 v119, v90, v62
	v_sub_f32_e32 v120, v90, v64
	v_add_u32_e32 v90, s19, v180
	v_add_u32_e32 v110, v90, v181
	v_add_u32_e32 v121, v90, v182
	ds_read_b128 v[90:93], v110
	ds_read_b128 v[94:97], v110 offset:4096
	ds_read_b128 v[98:101], v121
	ds_read_b128 v[102:105], v121 offset:4096
	ds_read_b128 v[106:109], v110 offset:8192
	ds_read_b128 v[110:113], v110 offset:12288
	ds_read_b128 v[114:117], v121 offset:8192
	ds_read_b128 v[146:149], v121 offset:12288
	v_cndmask_b32_e64 v118, 0, -1.0, vcc
	v_cmp_ge_i32_e32 vcc, s20, v0
	s_nop 1
	v_cndmask_b32_e32 v118, 1.0, v118, vcc
	v_pk_mul_f32 v[162:163], v[132:133], v[118:119] op_sel_hi:[1,0]
	s_nop 0
	v_fma_f32 v118, v119, v163, v162
	v_sub_f32_e32 v172, v118, v135
	v_fma_f32 v118, v120, v163, v162
	v_sub_f32_e32 v194, v118, v134
	v_mul_f32_e32 v120, 0, v163
	v_mov_b32_e32 v121, v163
	v_pk_add_f32 v[118:119], v[120:121], v[172:173] op_sel_hi:[1,0]
	v_pk_add_f32 v[150:151], v[120:121], v[194:195] op_sel_hi:[1,0]
	v_pk_fma_f32 v[120:121], v[162:163], s[30:31], v[172:173] op_sel:[1,0,0] op_sel_hi:[1,1,0]
	v_pk_fma_f32 v[152:153], v[162:163], s[30:31], v[194:195] op_sel:[1,0,0] op_sel_hi:[1,1,0]
	v_pk_fma_f32 v[156:157], v[162:163], s[96:97], v[172:173] op_sel:[1,0,0] op_sel_hi:[1,1,0]
	v_pk_fma_f32 v[154:155], v[162:163], s[26:27], v[172:173] op_sel:[1,0,0] op_sel_hi:[1,1,0]
	v_pk_fma_f32 v[160:161], v[162:163], s[96:97], v[194:195] op_sel:[1,0,0] op_sel_hi:[1,1,0]
	v_pk_fma_f32 v[158:159], v[162:163], s[26:27], v[194:195] op_sel:[1,0,0] op_sel_hi:[1,1,0]
	v_pk_fma_f32 v[170:171], v[162:163], s[88:89], v[172:173] op_sel:[1,0,0] op_sel_hi:[1,1,0]
	v_pk_fma_f32 v[168:169], v[162:163], s[98:99], v[172:173] op_sel:[1,0,0] op_sel_hi:[1,1,0]
	v_pk_fma_f32 v[188:189], v[162:163], s[88:89], v[194:195] op_sel:[1,0,0] op_sel_hi:[1,1,0]
	v_pk_fma_f32 v[186:187], v[162:163], s[98:99], v[194:195] op_sel:[1,0,0] op_sel_hi:[1,1,0]
	v_pk_fma_f32 v[192:193], v[162:163], s[82:83], v[172:173] op_sel:[1,0,0] op_sel_hi:[1,1,0]
	v_pk_fma_f32 v[190:191], v[162:163], s[0:1], v[172:173] op_sel:[1,0,0] op_sel_hi:[1,1,0]
	v_pk_fma_f32 v[196:197], v[162:163], s[82:83], v[194:195] op_sel:[1,0,0] op_sel_hi:[1,1,0]
	v_pk_fma_f32 v[194:195], v[162:163], s[0:1], v[194:195] op_sel:[1,0,0] op_sel_hi:[1,1,0]
	s_waitcnt lgkmcnt(0)
	s_setprio 1
	v_mfma_f32_16x16x32_bf16 v[118:121], v[90:93], v[6:9], v[118:121]
	v_mfma_f32_16x16x32_bf16 v[150:153], v[90:93], v[14:17], v[150:153]
	v_mfma_f32_16x16x32_bf16 v[154:157], v[94:97], v[6:9], v[154:157]
	v_mfma_f32_16x16x32_bf16 v[94:97], v[94:97], v[14:17], v[158:161]
	v_mfma_f32_16x16x32_bf16 v[158:161], v[106:109], v[6:9], v[168:171]
	v_mfma_f32_16x16x32_bf16 v[168:171], v[106:109], v[14:17], v[186:189]
	v_mfma_f32_16x16x32_bf16 v[186:189], v[110:113], v[6:9], v[190:193]
	v_mfma_f32_16x16x32_bf16 v[190:193], v[110:113], v[14:17], v[194:197]
	v_mfma_f32_16x16x32_bf16 v[90:93], v[98:101], v[10:13], v[118:121]
	v_mfma_f32_16x16x32_bf16 v[110:113], v[98:101], v[18:21], v[150:153]
	v_mfma_f32_16x16x32_bf16 v[118:121], v[102:105], v[10:13], v[154:157]
	v_mfma_f32_16x16x32_bf16 v[106:109], v[102:105], v[18:21], v[94:97]
	v_mfma_f32_16x16x32_bf16 v[98:101], v[114:117], v[10:13], v[158:161]
	v_mfma_f32_16x16x32_bf16 v[102:105], v[114:117], v[18:21], v[168:171]
	v_mfma_f32_16x16x32_bf16 v[114:117], v[146:149], v[10:13], v[186:189]
	v_mfma_f32_16x16x32_bf16 v[94:97], v[146:149], v[18:21], v[190:193]
	s_setprio 0
	v_cmp_ne_u32_e32 vcc, s20, v0
	s_and_saveexec_b64 s[2:3], vcc
	s_xor_b64 s[2:3], exec, s[2:3]
	s_cbranch_execz .LBB0_213
	s_cmp_lg_u32 s20, 1
	s_cbranch_scc1 .LBB0_213
	v_mov_b32_e32 v93, 0xf149f2ca
	v_mov_b32_e32 v92, v93
	v_mov_b32_e32 v91, v93
	v_mov_b32_e32 v90, v93
	v_mov_b32_e32 v113, v93
	v_mov_b32_e32 v112, v93
	v_mov_b32_e32 v111, v93
	v_mov_b32_e32 v110, v93
	v_mov_b32_e32 v121, v93
	v_mov_b32_e32 v120, v93
	v_mov_b32_e32 v119, v93
	v_mov_b32_e32 v118, v93
	v_mov_b32_e32 v109, v93
	v_mov_b32_e32 v108, v93
	v_mov_b32_e32 v107, v93
	v_mov_b32_e32 v106, v93
	v_mov_b32_e32 v101, v93
	v_mov_b32_e32 v100, v93
	v_mov_b32_e32 v99, v93
	v_mov_b32_e32 v98, v93
	v_mov_b32_e32 v105, v93
	v_mov_b32_e32 v104, v93
	v_mov_b32_e32 v103, v93
	v_mov_b32_e32 v102, v93

; DEVI void attn_unit(const Params& p, char* lds, int au) {
;     ...
; #pragma unroll
;     for (int qb = 0; qb < 2; ++qb) {
;       u32x4 t0, t1;
; #pragma unroll
;       for (int kb = 0; kb < 4; ++kb) {
;         f32x4 e;
;         e[0] = __builtin_amdgcn_exp2f(sc[kb][qb][0]);
;         e[1] = __builtin_amdgcn_exp2f(sc[kb][qb][1]);
;         e[2] = __builtin_amdgcn_exp2f(sc[kb][qb][2]);
;         e[3] = __builtin_amdgcn_exp2f(sc[kb][qb][3]);
;         lsum[qb] += e;
;         uint32_t w0 = pk2(e[0], e[1]), w1 = pk2(e[2], e[3]);
;         if (kb == 0) { t0[0] = w0; t0[1] = w1; }
;         if (kb == 1) { t0[2] = w0; t0[3] = w1; }
;         if (kb == 2) { t1[0] = w0; t1[1] = w1; }
;         if (kb == 3) { t1[2] = w0; t1[3] = w1; }
;       }
;       pf[qb][0] = __builtin_bit_cast(bf16x8, t0);
;       pf[qb][1] = __builtin_bit_cast(bf16x8, t1);
;     }
;     if (!typeB) PVSTEP(lds + 32768 + vcur * 16384);
.LBB0_217:
	v_exp_f32_e32 v146, v90
	v_exp_f32_e32 v147, v91
	v_exp_f32_e32 v148, v92
	v_exp_f32_e32 v149, v93
	v_exp_f32_e32 v118, v118
	v_exp_f32_e32 v119, v119
	v_exp_f32_e32 v120, v120
	v_exp_f32_e32 v121, v121
	v_exp_f32_e32 v150, v98
	v_exp_f32_e32 v151, v99
	v_exp_f32_e32 v152, v100
	v_exp_f32_e32 v153, v101
	v_exp_f32_e32 v114, v114
	v_exp_f32_e32 v115, v115
	v_exp_f32_e32 v116, v116
	v_exp_f32_e32 v117, v117
	v_exp_f32_e32 v154, v110
	v_exp_f32_e32 v155, v111
	v_exp_f32_e32 v156, v112
	v_exp_f32_e32 v157, v113
	v_exp_f32_e32 v106, v106
	v_exp_f32_e32 v107, v107
	v_exp_f32_e32 v108, v108
	v_exp_f32_e32 v109, v109
	v_exp_f32_e32 v158, v102
	v_exp_f32_e32 v159, v103
	v_exp_f32_e32 v160, v104
	v_exp_f32_e32 v161, v105
	v_exp_f32_e32 v94, v94
	v_exp_f32_e32 v95, v95
	v_exp_f32_e32 v96, v96
	v_exp_f32_e32 v97, v97
	v_cvt_pk_bf16_f32 v90, v146, v147
	v_cvt_pk_bf16_f32 v91, v148, v149
	v_cvt_pk_bf16_f32 v92, v118, v119
	v_cvt_pk_bf16_f32 v93, v120, v121
	v_cvt_pk_bf16_f32 v98, v150, v151
	v_cvt_pk_bf16_f32 v99, v152, v153
	v_cvt_pk_bf16_f32 v100, v114, v115
	v_cvt_pk_bf16_f32 v101, v116, v117
	v_cvt_pk_bf16_f32 v110, v154, v155
	v_cvt_pk_bf16_f32 v111, v156, v157
	v_cvt_pk_bf16_f32 v112, v106, v107
	v_cvt_pk_bf16_f32 v113, v108, v109
	v_cvt_pk_bf16_f32 v102, v158, v159
	v_cvt_pk_bf16_f32 v103, v160, v161
	v_cvt_pk_bf16_f32 v104, v94, v95
	s_and_b64 vcc, exec, s[12:13]
	v_cvt_pk_bf16_f32 v105, v96, v97
	s_cbranch_vccnz .LBB0_219
	s_waitcnt lgkmcnt(4)
	s_setprio 1
	v_mfma_f32_16x16x32_bf16 v[82:85], v[168:171], v[90:93], v[82:85]
	v_mfma_f32_16x16x32_bf16 v[78:81], v[168:171], v[110:113], v[78:81]
	v_mfma_f32_16x16x32_bf16 v[74:77], v[186:189], v[90:93], v[74:77]
	v_mfma_f32_16x16x32_bf16 v[70:73], v[186:189], v[110:113], v[70:73]
	v_mfma_f32_16x16x32_bf16 v[66:69], v[198:201], v[90:93], v[66:69]
	v_mfma_f32_16x16x32_bf16 v[58:61], v[198:201], v[110:113], v[58:61]
	v_mfma_f32_16x16x32_bf16 v[54:57], v[202:205], v[90:93], v[54:57]
	v_mfma_f32_16x16x32_bf16 v[50:53], v[202:205], v[110:113], v[50:53]
	ds_read_b128 v[168:171], v163 offset:40960
	ds_read_b128 v[186:189], v163 offset:43008
	ds_read_b128 v[198:201], v163 offset:45056
	ds_read_b128 v[202:205], v163 offset:47104
	s_waitcnt lgkmcnt(4)
	v_mfma_f32_16x16x32_bf16 v[82:85], v[190:193], v[98:101], v[82:85]
	v_mfma_f32_16x16x32_bf16 v[78:81], v[190:193], v[102:105], v[78:81]
	v_mfma_f32_16x16x32_bf16 v[74:77], v[194:197], v[98:101], v[74:77]
	v_mfma_f32_16x16x32_bf16 v[70:73], v[194:197], v[102:105], v[70:73]
	v_mfma_f32_16x16x32_bf16 v[66:69], v[206:209], v[98:101], v[66:69]
	v_mfma_f32_16x16x32_bf16 v[58:61], v[206:209], v[102:105], v[58:61]
	v_mfma_f32_16x16x32_bf16 v[54:57], v[210:213], v[98:101], v[54:57]
	v_mfma_f32_16x16x32_bf16 v[50:53], v[210:213], v[102:105], v[50:53]
	ds_read_b128 v[190:193], v162 offset:40960
	ds_read_b128 v[194:197], v162 offset:43008
	ds_read_b128 v[206:209], v162 offset:45056
	ds_read_b128 v[210:213], v162 offset:47104
	s_waitcnt lgkmcnt(4)
	v_mfma_f32_16x16x32_bf16 v[46:49], v[168:171], v[90:93], v[46:49]
	v_mfma_f32_16x16x32_bf16 v[42:45], v[168:171], v[110:113], v[42:45]
	v_mfma_f32_16x16x32_bf16 v[38:41], v[186:189], v[90:93], v[38:41]
	v_mfma_f32_16x16x32_bf16 v[34:37], v[186:189], v[110:113], v[34:37]
	v_mfma_f32_16x16x32_bf16 v[30:33], v[198:201], v[90:93], v[30:33]
	v_mfma_f32_16x16x32_bf16 v[26:29], v[198:201], v[110:113], v[26:29]
	v_mfma_f32_16x16x32_bf16 v[22:25], v[202:205], v[90:93], v[22:25]
	v_mfma_f32_16x16x32_bf16 v[2:5], v[202:205], v[110:113], v[2:5]
	s_waitcnt lgkmcnt(0)
	v_mfma_f32_16x16x32_bf16 v[46:49], v[190:193], v[98:101], v[46:49]
	v_mfma_f32_16x16x32_bf16 v[42:45], v[190:193], v[102:105], v[42:45]
	v_mfma_f32_16x16x32_bf16 v[38:41], v[194:197], v[98:101], v[38:41]
	v_mfma_f32_16x16x32_bf16 v[34:37], v[194:197], v[102:105], v[34:37]
	v_mfma_f32_16x16x32_bf16 v[30:33], v[206:209], v[98:101], v[30:33]
	v_mfma_f32_16x16x32_bf16 v[26:29], v[206:209], v[102:105], v[26:29]
	v_mfma_f32_16x16x32_bf16 v[22:25], v[210:213], v[98:101], v[22:25]
	v_mfma_f32_16x16x32_bf16 v[2:5], v[210:213], v[102:105], v[2:5]
	s_setprio 0
